# MLA attention loop restructured: PV(i-1)+QK(i) | barrier | softmax(i)+staging | barrier, 3 LDS slots, waves 4-7 one barrier behind; deeper LDS prefetch for QK and PV fragments
# baseline (speedup 1.0000x reference)
; #define LAS __attribute__((address_space(3)))
; DI unsigned pk2(float lo, float hi) { f32x2_t v = {lo, hi}; bf16x2_t b = __builtin_convertvector(v, bf16x2_t); return __builtin_bit_cast(unsigned, b); }
; #define MFMA32(a, b, c) __builtin_amdgcn_mfma_f32_32x32x16_bf16((a), (b), (c), 0, 0, 0)
; template <int MODE> DI void attn_unit(int b, int qb, const bf16* Qb, int qpitch, const bf16* Kb, int kpitch, const bf16* VT, bf16* O, float* ssq, ...
;     ...
;             const LAS unsigned char* vb = lds + VOFF + buf * VSZ + r32 * 136 + 8 * hi;
; #pragma unroll
;             for (int s4 = 0; s4 < 4; ++s4) {
;                 v4u pw;
;                 if (s4 == 0) { pw.x = pk2(p0[0], p0[1]); pw.y = pk2(p0[2], p0[3]); pw.z = pk2(p0[4], p0[5]); pw.w = pk2(p0[6], p0[7]); }
;                 if (s4 == 1) { pw.x = pk2(p0[8], p0[9]); pw.y = pk2(p0[10], p0[11]); pw.z = pk2(p0[12], p0[13]); pw.w = pk2(p0[14], p0[15]); }
;                 if (s4 == 2) { pw.x = pk2(p1[0], p1[1]); pw.y = pk2(p1[2], p1[3]); pw.z = pk2(p1[4], p1[5]); pw.w = pk2(p1[6], p1[7]); }
;                 if (s4 == 3) { pw.x = pk2(p1[8], p1[9]); pw.y = pk2(p1[10], p1[11]); pw.z = pk2(p1[12], p1[13]); pw.w = pk2(p1[14], p1[15]); }
;                 const v8s pf = __builtin_bit_cast(v8s, pw);
;                 const v2u a0 = *(const LAS v2u*)(vb + 32 * s4), a1 = *(const LAS v2u*)(vb + 32 * s4 + 16);
;                 const v2u c0 = *(const LAS v2u*)(vb + 32 * 136 + 32 * s4), c1 = *(const LAS v2u*)(vb + 32 * 136 + 32 * s4 + 16);
;                 const v4u va = {a0.x, a0.y, a1.x, a1.y}, vc2 = {c0.x, c0.y, c1.x, c1.y};
;                 o0 = MFMA32(__builtin_bit_cast(v8s, va), pf, o0);
;                 o1 = MFMA32(__builtin_bit_cast(v8s, vc2), pf, o1);
;             }
.Lmla_nov:
	s_cmp_eq_u32 s101, 0
	s_cbranch_scc1 .Lmla_nopv
	s_lshr_b32 s24, s100, 8
	s_and_b32 s24, s24, 0xffffff00
	v_add_u32_e32 v41, s24, v195
	v_add_u32_e32 v62, 0x1000, v41
	ds_read2_b64 v[50:53], v41 offset1:2
	ds_read2_b64 v[58:61], v62 offset0:32 offset1:34
	ds_read2_b64 v[54:57], v41 offset0:4 offset1:6
	ds_read2_b64 v[210:213], v62 offset0:36 offset1:38
	ds_read2_b64 v[236:239], v41 offset0:8 offset1:10
	s_waitcnt lgkmcnt(4)
	v_mfma_f32_32x32x16_bf16 v[0:15], v[50:53], v[42:45], v[0:15]
	s_waitcnt lgkmcnt(3)
	v_mfma_f32_32x32x16_bf16 v[16:31], v[58:61], v[42:45], v[16:31]
	ds_read2_b64 v[42:45], v62 offset0:40 offset1:42
	ds_read2_b64 v[50:53], v41 offset0:12 offset1:14
	ds_read2_b64 v[58:61], v62 offset0:44 offset1:46
	s_waitcnt lgkmcnt(5)
	v_mfma_f32_32x32x16_bf16 v[0:15], v[54:57], v[46:49], v[0:15]
	s_waitcnt lgkmcnt(4)
	v_mfma_f32_32x32x16_bf16 v[16:31], v[210:213], v[46:49], v[16:31]
	s_waitcnt lgkmcnt(3)
	v_mfma_f32_32x32x16_bf16 v[0:15], v[236:239], v[36:39], v[0:15]
	s_waitcnt lgkmcnt(2)
	v_mfma_f32_32x32x16_bf16 v[16:31], v[42:45], v[36:39], v[16:31]
	s_waitcnt lgkmcnt(1)
	v_mfma_f32_32x32x16_bf16 v[0:15], v[50:53], v[32:35], v[0:15]
	s_waitcnt lgkmcnt(0)
	v_mfma_f32_32x32x16_bf16 v[16:31], v[58:61], v[32:35], v[16:31]

; #define LAS __attribute__((address_space(3)))
; DI unsigned pk2(float lo, float hi) { f32x2_t v = {lo, hi}; bf16x2_t b = __builtin_convertvector(v, bf16x2_t); return __builtin_bit_cast(unsigned, b); }
; #define MFMA32(a, b, c) __builtin_amdgcn_mfma_f32_32x32x16_bf16((a), (b), (c), 0, 0, 0)
; template <int MODE> DI void attn_unit(int b, int qb, const bf16* Qb, int qpitch, const bf16* Kb, int kpitch, const bf16* VT, bf16* O, float* ssq, ...
;     ...
;             const LAS unsigned char* vb = lds + VOFF + buf * VSZ + r32 * 136 + 8 * hi;
; #pragma unroll
;             for (int s4 = 0; s4 < 4; ++s4) {
;                 v4u pw;
;                 if (s4 == 0) { pw.x = pk2(p0[0], p0[1]); pw.y = pk2(p0[2], p0[3]); pw.z = pk2(p0[4], p0[5]); pw.w = pk2(p0[6], p0[7]); }
;                 if (s4 == 1) { pw.x = pk2(p0[8], p0[9]); pw.y = pk2(p0[10], p0[11]); pw.z = pk2(p0[12], p0[13]); pw.w = pk2(p0[14], p0[15]); }
;                 if (s4 == 2) { pw.x = pk2(p1[0], p1[1]); pw.y = pk2(p1[2], p1[3]); pw.z = pk2(p1[4], p1[5]); pw.w = pk2(p1[6], p1[7]); }
;                 if (s4 == 3) { pw.x = pk2(p1[8], p1[9]); pw.y = pk2(p1[10], p1[11]); pw.z = pk2(p1[12], p1[13]); pw.w = pk2(p1[14], p1[15]); }
;                 const v8s pf = __builtin_bit_cast(v8s, pw);
;                 const v2u a0 = *(const LAS v2u*)(vb + 32 * s4), a1 = *(const LAS v2u*)(vb + 32 * s4 + 16);
;                 const v2u c0 = *(const LAS v2u*)(vb + 32 * 136 + 32 * s4), c1 = *(const LAS v2u*)(vb + 32 * 136 + 32 * s4 + 16);
;                 const v4u va = {a0.x, a0.y, a1.x, a1.y}, vc2 = {c0.x, c0.y, c1.x, c1.y};
;                 o0 = MFMA32(__builtin_bit_cast(v8s, va), pf, o0);
;                 o1 = MFMA32(__builtin_bit_cast(v8s, vc2), pf, o1);
;             }
.Lmla_nostv:
	s_add_i32 s72, s72, 64
	s_add_i32 s74, s74, 1
	v_lshl_add_u64 v[188:189], v[188:189], 0, s[92:93]
	v_lshl_add_u64 v[186:187], v[186:187], 0, s[80:81]
	v_lshl_add_u64 v[184:185], v[184:185], 0, s[80:81]
	s_mov_b32 s24, s98
	s_mov_b32 s98, s99
	s_mov_b32 s99, s100
	s_mov_b32 s100, s24
	s_cmp_eq_u32 s69, s72
	s_waitcnt lgkmcnt(0)
	s_barrier
	s_cbranch_scc0 .Lmla_loop
	s_cmp_eq_u32 s101, 0
	s_cbranch_scc1 .Lmla_nopv2
	s_lshr_b32 s24, s100, 8
	s_and_b32 s24, s24, 0xffffff00
	v_add_u32_e32 v41, s24, v195
	v_add_u32_e32 v62, 0x1000, v41
	ds_read2_b64 v[50:53], v41 offset1:2
	ds_read2_b64 v[58:61], v62 offset0:32 offset1:34
	ds_read2_b64 v[54:57], v41 offset0:4 offset1:6
	ds_read2_b64 v[210:213], v62 offset0:36 offset1:38
	ds_read2_b64 v[236:239], v41 offset0:8 offset1:10
	s_waitcnt lgkmcnt(4)
	v_mfma_f32_32x32x16_bf16 v[0:15], v[50:53], v[42:45], v[0:15]
	s_waitcnt lgkmcnt(3)
	v_mfma_f32_32x32x16_bf16 v[16:31], v[58:61], v[42:45], v[16:31]
	ds_read2_b64 v[42:45], v62 offset0:40 offset1:42
	ds_read2_b64 v[50:53], v41 offset0:12 offset1:14
	ds_read2_b64 v[58:61], v62 offset0:44 offset1:46
	s_waitcnt lgkmcnt(5)
	v_mfma_f32_32x32x16_bf16 v[0:15], v[54:57], v[46:49], v[0:15]
	s_waitcnt lgkmcnt(4)
	v_mfma_f32_32x32x16_bf16 v[16:31], v[210:213], v[46:49], v[16:31]
	s_waitcnt lgkmcnt(3)
	v_mfma_f32_32x32x16_bf16 v[0:15], v[236:239], v[36:39], v[0:15]
	s_waitcnt lgkmcnt(2)
	v_mfma_f32_32x32x16_bf16 v[16:31], v[42:45], v[36:39], v[16:31]
	s_waitcnt lgkmcnt(1)
	v_mfma_f32_32x32x16_bf16 v[0:15], v[50:53], v[32:35], v[0:15]
	s_waitcnt lgkmcnt(0)
	v_mfma_f32_32x32x16_bf16 v[16:31], v[58:61], v[32:35], v[16:31]
	s_nop 7
	s_nop 3
